# ssm_endstates K-loop rewritten: 27 fragment loads in flight (distinct VGPRs, counted vmcnt) instead of one load + vmcnt(0) per MFMA
# speedup vs baseline: 1.0996x; 1.0083x over previous
; __device__ __forceinline__ void ssm_endstates(const Params& p, int l, char* lds) {
;     ...
;     for (int kk = 0; kk < 16; ++kk) {
;       const int ks = kh * 16 + kk;
;       h16x8 B = *(const h16x8*)(ub + (size_t)(ks * 2) * IWP);
; #pragma unroll
;       for (int mt = 0; mt < 8; ++mt) {
;         h16x8 A = *(const h16x8*)(W1 + ((size_t)(ks * 4 + (lane >> 4)) * 128 + mt * 16 + (lane & 15)) * 8);
;         acc[mt] = __builtin_amdgcn_mfma_f32_16x16x32_f16(A, B, acc[mt], 0, 0, 0);
;       }
;     }
.LBB0_620:
	v_lshl_add_u64 v[96:97], s[82:83], 0, v[50:51]
	v_add_co_u32_e64 v98, s[0:1], s91, v96
	v_lshl_add_u64 v[106:107], s[82:83], 0, v[52:53]
	s_nop 0
	v_addc_co_u32_e64 v99, s[0:1], 0, v97, s[0:1]
	global_load_dwordx4 v[116:119], v[98:99], off offset:2560
	global_load_dwordx4 v[152:155], v[106:107], off offset:-1024
	global_load_dwordx4 v[156:159], v[106:107], off offset:-768
	global_load_dwordx4 v[160:163], v[106:107], off offset:-512
	global_load_dwordx4 v[164:167], v[106:107], off offset:-256
	global_load_dwordx4 v[168:171], v[106:107], off
	global_load_dwordx4 v[172:175], v[106:107], off offset:256
	global_load_dwordx4 v[176:179], v[106:107], off offset:512
	global_load_dwordx4 v[180:183], v[106:107], off offset:768
	s_mov_b32 s0, 0xe87f000
	v_add_co_u32_e64 v100, s[0:1], s0, v96
	v_lshl_add_u64 v[108:109], s[82:83], 0, v[56:57]
	s_nop 0
	v_addc_co_u32_e64 v101, s[0:1], 0, v97, s[0:1]
	global_load_dwordx4 v[120:123], v[100:101], off offset:1536
	global_load_dwordx4 v[202:205], v[108:109], off offset:-1024
	global_load_dwordx4 v[206:209], v[108:109], off offset:-768
	global_load_dwordx4 v[210:213], v[108:109], off offset:-512
	global_load_dwordx4 v[214:217], v[108:109], off offset:-256
	global_load_dwordx4 v[218:221], v[108:109], off
	global_load_dwordx4 v[222:225], v[108:109], off offset:256
	global_load_dwordx4 v[226:229], v[108:109], off offset:512
	global_load_dwordx4 v[230:233], v[108:109], off offset:768
	s_mov_b32 s0, 0xe881000
	v_add_co_u32_e64 v102, s[0:1], s0, v96
	v_lshl_add_u64 v[110:111], s[82:83], 0, v[58:59]
	s_nop 0
	v_addc_co_u32_e64 v103, s[0:1], 0, v97, s[0:1]
	global_load_dwordx4 v[124:127], v[102:103], off offset:512
	global_load_dwordx4 v[234:237], v[110:111], off offset:-1024
	global_load_dwordx4 v[238:241], v[110:111], off offset:-768
	global_load_dwordx4 v[242:245], v[110:111], off offset:-512
	global_load_dwordx4 v[246:249], v[110:111], off offset:-256
	global_load_dwordx4 v[250:253], v[110:111], off
	global_load_dwordx4 v[132:135], v[110:111], off offset:256
	global_load_dwordx4 v[136:139], v[110:111], off offset:512
	global_load_dwordx4 v[184:187], v[110:111], off offset:768
	s_mov_b32 s0, 0xe882000
	v_add_co_u32_e64 v104, s[0:1], s0, v96
	v_lshl_add_u64 v[112:113], s[82:83], 0, v[54:55]
	s_nop 0
	v_addc_co_u32_e64 v105, s[0:1], 0, v97, s[0:1]
	v_lshl_add_u64 v[52:53], v[52:53], 0, s[96:97]
	v_lshl_add_u64 v[56:57], v[56:57], 0, s[96:97]
	v_lshl_add_u64 v[58:59], v[58:59], 0, s[96:97]
	v_lshl_add_u64 v[54:55], v[54:55], 0, s[96:97]
	s_mov_b64 s[0:1], 0x7000
	v_lshl_add_u64 v[50:51], v[50:51], 0, s[0:1]
	s_waitcnt vmcnt(18)
	v_mfma_f32_16x16x32_f16 v[2:5], v[152:155], v[116:119], v[2:5]
	v_mfma_f32_16x16x32_f16 v[34:37], v[156:159], v[116:119], v[34:37]
	v_mfma_f32_16x16x32_f16 v[26:29], v[160:163], v[116:119], v[26:29]
	v_mfma_f32_16x16x32_f16 v[22:25], v[164:167], v[116:119], v[22:25]
	v_mfma_f32_16x16x32_f16 v[18:21], v[168:171], v[116:119], v[18:21]
	v_mfma_f32_16x16x32_f16 v[14:17], v[172:175], v[116:119], v[14:17]
	v_mfma_f32_16x16x32_f16 v[10:13], v[176:179], v[116:119], v[10:13]
	v_mfma_f32_16x16x32_f16 v[6:9], v[180:183], v[116:119], v[6:9]
	global_load_dwordx4 v[116:119], v[104:105], off offset:3584
	global_load_dwordx4 v[152:155], v[112:113], off offset:-1024
	global_load_dwordx4 v[156:159], v[112:113], off offset:-768
	global_load_dwordx4 v[160:163], v[112:113], off offset:-512
	global_load_dwordx4 v[164:167], v[112:113], off offset:-256
	global_load_dwordx4 v[168:171], v[112:113], off
	global_load_dwordx4 v[172:175], v[112:113], off offset:256
	global_load_dwordx4 v[176:179], v[112:113], off offset:512
	global_load_dwordx4 v[180:183], v[112:113], off offset:768
	s_waitcnt vmcnt(18)
	v_mfma_f32_16x16x32_f16 v[2:5], v[202:205], v[120:123], v[2:5]
	v_mfma_f32_16x16x32_f16 v[34:37], v[206:209], v[120:123], v[34:37]
	v_mfma_f32_16x16x32_f16 v[26:29], v[210:213], v[120:123], v[26:29]
	v_mfma_f32_16x16x32_f16 v[22:25], v[214:217], v[120:123], v[22:25]
	v_mfma_f32_16x16x32_f16 v[18:21], v[218:221], v[120:123], v[18:21]
	v_mfma_f32_16x16x32_f16 v[14:17], v[222:225], v[120:123], v[14:17]
	v_mfma_f32_16x16x32_f16 v[10:13], v[226:229], v[120:123], v[10:13]
	v_mfma_f32_16x16x32_f16 v[6:9], v[230:233], v[120:123], v[6:9]
	s_waitcnt vmcnt(9)
	v_mfma_f32_16x16x32_f16 v[2:5], v[234:237], v[124:127], v[2:5]
	v_mfma_f32_16x16x32_f16 v[34:37], v[238:241], v[124:127], v[34:37]
	v_mfma_f32_16x16x32_f16 v[26:29], v[242:245], v[124:127], v[26:29]
	v_mfma_f32_16x16x32_f16 v[22:25], v[246:249], v[124:127], v[22:25]
	v_mfma_f32_16x16x32_f16 v[18:21], v[250:253], v[124:127], v[18:21]
	v_mfma_f32_16x16x32_f16 v[14:17], v[132:135], v[124:127], v[14:17]
	v_mfma_f32_16x16x32_f16 v[10:13], v[136:139], v[124:127], v[10:13]
	v_mfma_f32_16x16x32_f16 v[6:9], v[184:187], v[124:127], v[6:9]
	s_waitcnt vmcnt(0)
	v_mfma_f32_16x16x32_f16 v[2:5], v[152:155], v[116:119], v[2:5]
	v_mfma_f32_16x16x32_f16 v[34:37], v[156:159], v[116:119], v[34:37]
	v_mfma_f32_16x16x32_f16 v[26:29], v[160:163], v[116:119], v[26:29]
	v_mfma_f32_16x16x32_f16 v[22:25], v[164:167], v[116:119], v[22:25]
	v_mfma_f32_16x16x32_f16 v[18:21], v[168:171], v[116:119], v[18:21]
	v_mfma_f32_16x16x32_f16 v[14:17], v[172:175], v[116:119], v[14:17]
	v_mfma_f32_16x16x32_f16 v[10:13], v[176:179], v[116:119], v[10:13]
	v_mfma_f32_16x16x32_f16 v[6:9], v[180:183], v[116:119], v[6:9]
	s_add_i32 s3, s3, -4
	s_cmp_eq_u32 s3, 0
	s_cbranch_scc0 .LBB0_620
	s_barrier
	s_and_saveexec_b64 s[0:1], vcc
	s_cbranch_execz .LBB0_623
	ds_write_b128 v64, v[2:5]
	ds_write_b128 v64, v[34:37] offset:1024
	ds_write_b128 v64, v[26:29] offset:2048
	ds_write_b128 v64, v[22:25] offset:3072
	ds_write_b128 v64, v[18:21] offset:4096
	ds_write_b128 v64, v[14:17] offset:5120
	ds_write_b128 v64, v[10:13] offset:6144
	ds_write_b128 v64, v[6:9] offset:7168
